# grid seams: waiting workgroups and non-last leaders poll the cross-XCC arrival counter itself (target = (generation+1) * populated XCCs); release-generation word no longer used
# speedup vs baseline: 1.0334x; 1.0003x over previous
; __device__ __forceinline__ unsigned xb_ld(unsigned* p)              { return __hip_atomic_load(p, __ATOMIC_RELAXED, __HIP_MEMORY_SCOPE_AGENT); }
; __device__ __forceinline__ unsigned xb_add(unsigned* p, unsigned v) { return __hip_atomic_fetch_add(p, v, __ATOMIC_RELAXED, __HIP_MEMORY_SCOPE_AGENT); }
; #define XB_SPIN(cond, bar) do { unsigned _sp = 0; while (cond) { __builtin_amdgcn_s_sleep(1); \
;     if ((++_sp & 255u) == 0u) { if (xb_ld(&(bar)[XB_TMO])) break; if (_sp > XB_SPIN_CAP) { atomicAdd(&(bar)[XB_TMO], 1u); break; } } } } while (0)
; __device__ __forceinline__ void xcd_barrier(const XcdBarrier& b) {
;     ...
;         const unsigned old = xb_add(&bar[XB_XSUB(b.x)], 1u);
;         const unsigned gen = old / nloc;
;         if (old + 1u == (gen + 1u) * nloc) {
;             __builtin_amdgcn_fence(__ATOMIC_RELEASE, "agent");
;             asm volatile("s_waitcnt vmcnt(0)" ::: "memory");
;             const unsigned og = xb_add(&bar[XB_TOP], 1u);
;             const unsigned tg = og / nx;
;             if (og + 1u == (tg + 1u) * nx) xb_add(&bar[XB_TOPGEN], 1u);
;             else XB_SPIN(xb_ld(&bar[XB_TOPGEN]) == tg, bar);
;             __builtin_amdgcn_fence(__ATOMIC_ACQUIRE, "agent");
;             xb_add(&bar[XB_XGEN(b.x)], 1u);
;             asm volatile("s_waitcnt vmcnt(0)" ::: "memory");
;         } else {
;             XB_SPIN(xb_ld(&bar[XB_XGEN(b.x)]) == gen, bar);
;             __builtin_amdgcn_fence(__ATOMIC_ACQUIRE, "agent");
.LBB0_207:
	s_or_b64 exec, exec, s[14:15]
	v_cvt_f32_u32_e32 v5, v3
	s_waitcnt vmcnt(0)
	v_readfirstlane_b32 s0, v4
	v_sub_u32_e32 v4, 0, v3
	v_rcp_iflag_f32_e32 v5, v5
	v_add_u32_e32 v6, s0, v2
	v_mul_f32_e32 v5, 0x4f7ffffe, v5
	v_cvt_u32_f32_e32 v5, v5
	v_mul_lo_u32 v2, v4, v5
	v_mul_hi_u32 v2, v5, v2
	v_add_u32_e32 v2, v5, v2
	v_mul_hi_u32 v2, v6, v2
	v_mul_lo_u32 v4, v2, v3
	v_sub_u32_e32 v4, v6, v4
	v_add_u32_e32 v5, 1, v2
	v_cmp_ge_u32_e32 vcc, v4, v3
	s_nop 1
	v_cndmask_b32_e32 v2, v2, v5, vcc
	v_sub_u32_e32 v5, v4, v3
	v_cndmask_b32_e32 v4, v4, v5, vcc
	v_add_u32_e32 v5, 1, v2
	v_cmp_ge_u32_e32 vcc, v4, v3
	v_add_u32_e32 v4, 1, v6
	s_nop 0
	v_cndmask_b32_e32 v2, v2, v5, vcc
	v_mul_lo_u32 v5, v3, v2
	v_add_u32_e32 v3, v5, v3
	v_cmp_ne_u32_e32 vcc, v4, v3
	s_and_saveexec_b64 s[0:1], vcc
	s_xor_b64 s[12:13], exec, s[0:1]
	s_cbranch_execz .LBB0_221
	s_waitcnt lgkmcnt(0)
	v_add_u32_e32 v20, 1, v2
	v_mul_lo_u32 v20, v20, v1
	buffer_inv sc1
	s_add_u32 s18, s26, 0xff03400
	s_addc_u32 s19, s27, 0
	v_mov_b32_e32 v1, 0
	global_load_dword v1, v1, s[18:19] sc1
	s_waitcnt vmcnt(0)
	v_cmp_lt_u32_e32 vcc, v1, v20
	s_and_saveexec_b64 s[14:15], vcc
	s_cbranch_execz .LBB0_220
	s_add_u32 s16, s26, 0xff00200
	s_addc_u32 s17, s27, 0
	s_mov_b32 s0, 1
	s_mov_b64 s[20:21], 0
	v_mov_b32_e32 v1, 0
	s_branch .LBB0_211

; __device__ __forceinline__ unsigned xb_ld(unsigned* p)              { return __hip_atomic_load(p, __ATOMIC_RELAXED, __HIP_MEMORY_SCOPE_AGENT); }
; #define XB_SPIN(cond, bar) do { unsigned _sp = 0; while (cond) { __builtin_amdgcn_s_sleep(1); \
;     if ((++_sp & 255u) == 0u) { if (xb_ld(&(bar)[XB_TMO])) break; if (_sp > XB_SPIN_CAP) { atomicAdd(&(bar)[XB_TMO], 1u); break; } } } } while (0)
; __device__ __forceinline__ void xcd_barrier(const XcdBarrier& b) {
;     ...
;             XB_SPIN(xb_ld(&bar[XB_XGEN(b.x)]) == gen, bar);
.LBB0_215:
	global_load_dword v3, v1, s[18:19] sc1
	s_add_i32 s0, s0, 1
	s_mov_b64 s[40:41], -1
	s_waitcnt vmcnt(0)
	v_cmp_ge_u32_e32 vcc, v3, v20
	s_orn2_b64 s[36:37], vcc, exec
	s_branch .LBB0_210

; __device__ __forceinline__ unsigned xb_ld(unsigned* p)              { return __hip_atomic_load(p, __ATOMIC_RELAXED, __HIP_MEMORY_SCOPE_AGENT); }
; __device__ __forceinline__ unsigned xb_add(unsigned* p, unsigned v) { return __hip_atomic_fetch_add(p, v, __ATOMIC_RELAXED, __HIP_MEMORY_SCOPE_AGENT); }
; #define XB_SPIN(cond, bar) do { unsigned _sp = 0; while (cond) { __builtin_amdgcn_s_sleep(1); \
;     if ((++_sp & 255u) == 0u) { if (xb_ld(&(bar)[XB_TMO])) break; if (_sp > XB_SPIN_CAP) { atomicAdd(&(bar)[XB_TMO], 1u); break; } } } } while (0)
; __device__ __forceinline__ void xcd_barrier(const XcdBarrier& b) {
;     ...
;             const unsigned og = xb_add(&bar[XB_TOP], 1u);
;             const unsigned tg = og / nx;
;             if (og + 1u == (tg + 1u) * nx) xb_add(&bar[XB_TOPGEN], 1u);
;             else XB_SPIN(xb_ld(&bar[XB_TOPGEN]) == tg, bar);
.LBB0_224:
	s_or_b64 exec, exec, s[14:15]
	v_cvt_f32_u32_e32 v4, v1
	s_waitcnt vmcnt(0)
	v_readfirstlane_b32 s0, v3
	s_add_u32 s14, s26, 0xff03400
	s_addc_u32 s15, s27, 0
	v_rcp_iflag_f32_e32 v4, v4
	v_add_u32_e32 v2, s0, v2
	v_add_u32_e32 v5, 1, v2
	s_mov_b64 s[16:17], -1
	v_mul_f32_e32 v3, 0x4f7ffffe, v4
	v_cvt_u32_f32_e32 v3, v3
	v_sub_u32_e32 v4, 0, v1
	v_mul_lo_u32 v4, v4, v3
	v_mul_hi_u32 v4, v3, v4
	v_add_u32_e32 v3, v3, v4
	v_mul_hi_u32 v3, v2, v3
	v_mul_lo_u32 v4, v3, v1
	v_sub_u32_e32 v2, v2, v4
	v_add_u32_e32 v6, 1, v3
	v_cmp_ge_u32_e32 vcc, v2, v1
	v_sub_u32_e32 v4, v2, v1
	s_nop 0
	v_cndmask_b32_e32 v3, v3, v6, vcc
	v_cndmask_b32_e32 v2, v2, v4, vcc
	v_add_u32_e32 v4, 1, v3
	v_cmp_ge_u32_e32 vcc, v2, v1
	s_nop 1
	v_cndmask_b32_e32 v4, v3, v4, vcc
	v_mul_lo_u32 v2, v1, v4
	v_add_u32_e32 v1, v2, v1
	v_cmp_ne_u32_e32 vcc, v5, v1
	v_mov_b64_e32 v[2:3], s[14:15]
	s_and_saveexec_b64 s[12:13], vcc
	s_cbranch_execz .LBB0_236
	v_mov_b32_e32 v20, v1
	v_mov_b32_e32 v1, 0
	global_load_dword v2, v1, s[14:15] sc1
	s_mov_b64 s[20:21], 0
	s_waitcnt vmcnt(0)
	v_cmp_lt_u32_e32 vcc, v2, v20
	s_and_saveexec_b64 s[18:19], vcc
	s_cbranch_execz .LBB0_235
	s_add_u32 s16, s26, 0xff00200
	s_addc_u32 s17, s27, 0
	s_mov_b32 s0, 1
	s_branch .LBB0_228

; __device__ __forceinline__ unsigned xb_ld(unsigned* p)              { return __hip_atomic_load(p, __ATOMIC_RELAXED, __HIP_MEMORY_SCOPE_AGENT); }
; #define XB_SPIN(cond, bar) do { unsigned _sp = 0; while (cond) { __builtin_amdgcn_s_sleep(1); \
;     if ((++_sp & 255u) == 0u) { if (xb_ld(&(bar)[XB_TMO])) break; if (_sp > XB_SPIN_CAP) { atomicAdd(&(bar)[XB_TMO], 1u); break; } } } } while (0)
; __device__ __forceinline__ void xcd_barrier(const XcdBarrier& b) {
;     ...
;             else XB_SPIN(xb_ld(&bar[XB_TOPGEN]) == tg, bar);
.LBB0_232:
	global_load_dword v2, v1, s[14:15] sc1
	s_add_i32 s0, s0, 1
	s_mov_b64 s[36:37], -1
	s_waitcnt vmcnt(0)
	v_cmp_ge_u32_e32 vcc, v2, v20
	s_orn2_b64 s[42:43], vcc, exec
	s_branch .LBB0_227

; __device__ __forceinline__ unsigned xb_ld(unsigned* p)              { return __hip_atomic_load(p, __ATOMIC_RELAXED, __HIP_MEMORY_SCOPE_AGENT); }
; __device__ __forceinline__ unsigned xb_add(unsigned* p, unsigned v) { return __hip_atomic_fetch_add(p, v, __ATOMIC_RELAXED, __HIP_MEMORY_SCOPE_AGENT); }
; #define XB_SPIN(cond, bar) do { unsigned _sp = 0; while (cond) { __builtin_amdgcn_s_sleep(1); \
;     if ((++_sp & 255u) == 0u) { if (xb_ld(&(bar)[XB_TMO])) break; if (_sp > XB_SPIN_CAP) { atomicAdd(&(bar)[XB_TMO], 1u); break; } } } } while (0)
; __device__ __forceinline__ void xcd_barrier(const XcdBarrier& b) {
;     ...
;             if (og + 1u == (tg + 1u) * nx) xb_add(&bar[XB_TOPGEN], 1u);
;             else XB_SPIN(xb_ld(&bar[XB_TOPGEN]) == tg, bar);
;             __builtin_amdgcn_fence(__ATOMIC_ACQUIRE, "agent");
;             xb_add(&bar[XB_XGEN(b.x)], 1u);
.LBB0_236:
	s_or_b64 exec, exec, s[12:13]
	s_and_saveexec_b64 s[12:13], s[16:17]
	s_cbranch_execz .LBB0_238
	v_mov_b32_e32 v1, 1
.LBB0_238:
	s_or_b64 exec, exec, s[12:13]
	s_mov_b64 s[12:13], exec
	v_mbcnt_lo_u32_b32 v1, s12, 0
	v_mbcnt_hi_u32_b32 v1, s13, v1
	v_cmp_eq_u32_e32 vcc, 0, v1
	s_waitcnt vmcnt(0) lgkmcnt(0)
	s_and_saveexec_b64 s[14:15], vcc
	s_cbranch_execz .LBB0_240
	s_bcnt1_i32_b64 s0, s[12:13]
	v_mov_b32_e32 v1, 0x2000
	v_mov_b32_e32 v2, s0

; __device__ __forceinline__ unsigned xb_ld(unsigned* p)              { return __hip_atomic_load(p, __ATOMIC_RELAXED, __HIP_MEMORY_SCOPE_AGENT); }
; __device__ __forceinline__ unsigned xb_add(unsigned* p, unsigned v) { return __hip_atomic_fetch_add(p, v, __ATOMIC_RELAXED, __HIP_MEMORY_SCOPE_AGENT); }
; #define XB_SPIN(cond, bar) do { unsigned _sp = 0; while (cond) { __builtin_amdgcn_s_sleep(1); \
;     if ((++_sp & 255u) == 0u) { if (xb_ld(&(bar)[XB_TMO])) break; if (_sp > XB_SPIN_CAP) { atomicAdd(&(bar)[XB_TMO], 1u); break; } } } } while (0)
; __device__ __forceinline__ void xcd_barrier(const XcdBarrier& b) {
;     ...
;             if (og + 1u == (tg + 1u) * nx) xb_add(&bar[XB_TOPGEN], 1u);
;             else XB_SPIN(xb_ld(&bar[XB_TOPGEN]) == tg, bar);
;             __builtin_amdgcn_fence(__ATOMIC_ACQUIRE, "agent");
;             xb_add(&bar[XB_XGEN(b.x)], 1u);
.LBB0_463:
	s_or_b64 exec, exec, s[12:13]
	s_and_saveexec_b64 s[12:13], s[16:17]
	s_cbranch_execz .LBB0_465
	v_mov_b32_e32 v1, 1
.LBB0_465:
	s_or_b64 exec, exec, s[12:13]
	s_mov_b64 s[12:13], exec
	v_mbcnt_lo_u32_b32 v1, s12, 0
	v_mbcnt_hi_u32_b32 v1, s13, v1
	v_cmp_eq_u32_e32 vcc, 0, v1
	s_waitcnt vmcnt(0)
	s_and_saveexec_b64 s[14:15], vcc
	s_cbranch_execz .LBB0_467
	s_bcnt1_i32_b64 s0, s[12:13]
	v_mov_b32_e32 v1, 0x2000
	v_mov_b32_e32 v2, s0

; __device__ __forceinline__ unsigned xb_ld(unsigned* p)              { return __hip_atomic_load(p, __ATOMIC_RELAXED, __HIP_MEMORY_SCOPE_AGENT); }
; #define XB_SPIN(cond, bar) do { unsigned _sp = 0; while (cond) { __builtin_amdgcn_s_sleep(1); \
;     if ((++_sp & 255u) == 0u) { if (xb_ld(&(bar)[XB_TMO])) break; if (_sp > XB_SPIN_CAP) { atomicAdd(&(bar)[XB_TMO], 1u); break; } } } } while (0)
; __device__ __forceinline__ void xcd_barrier(const XcdBarrier& b) {
;     ...
;             XB_SPIN(xb_ld(&bar[XB_XGEN(b.x)]) == gen, bar);
.LBB0_539:
	global_load_dword v3, v1, s[18:19] sc1
	s_add_i32 s0, s0, 1
	s_mov_b64 s[44:45], -1
	s_waitcnt vmcnt(0)
	v_cmp_ge_u32_e32 vcc, v3, v20
	s_orn2_b64 s[40:41], vcc, exec
	s_branch .LBB0_534

; __device__ __forceinline__ unsigned xb_ld(unsigned* p)              { return __hip_atomic_load(p, __ATOMIC_RELAXED, __HIP_MEMORY_SCOPE_AGENT); }
; #define XB_SPIN(cond, bar) do { unsigned _sp = 0; while (cond) { __builtin_amdgcn_s_sleep(1); \
;     if ((++_sp & 255u) == 0u) { if (xb_ld(&(bar)[XB_TMO])) break; if (_sp > XB_SPIN_CAP) { atomicAdd(&(bar)[XB_TMO], 1u); break; } } } } while (0)
; __device__ __forceinline__ void xcd_barrier(const XcdBarrier& b) {
;     ...
;             else XB_SPIN(xb_ld(&bar[XB_TOPGEN]) == tg, bar);
.LBB0_556:
	global_load_dword v2, v1, s[14:15] sc1
	s_add_i32 s0, s0, 1
	s_mov_b64 s[40:41], -1
	s_waitcnt vmcnt(0)
	v_cmp_ge_u32_e32 vcc, v2, v20
	s_orn2_b64 s[46:47], vcc, exec
	s_branch .LBB0_551

; __device__ __forceinline__ unsigned xb_ld(unsigned* p)              { return __hip_atomic_load(p, __ATOMIC_RELAXED, __HIP_MEMORY_SCOPE_AGENT); }
; __device__ __forceinline__ unsigned xb_add(unsigned* p, unsigned v) { return __hip_atomic_fetch_add(p, v, __ATOMIC_RELAXED, __HIP_MEMORY_SCOPE_AGENT); }
; #define XB_SPIN(cond, bar) do { unsigned _sp = 0; while (cond) { __builtin_amdgcn_s_sleep(1); \
;     if ((++_sp & 255u) == 0u) { if (xb_ld(&(bar)[XB_TMO])) break; if (_sp > XB_SPIN_CAP) { atomicAdd(&(bar)[XB_TMO], 1u); break; } } } } while (0)
; __device__ __forceinline__ void xcd_barrier(const XcdBarrier& b) {
;     ...
;             if (og + 1u == (tg + 1u) * nx) xb_add(&bar[XB_TOPGEN], 1u);
;             else XB_SPIN(xb_ld(&bar[XB_TOPGEN]) == tg, bar);
;             __builtin_amdgcn_fence(__ATOMIC_ACQUIRE, "agent");
;             xb_add(&bar[XB_XGEN(b.x)], 1u);
.LBB0_560:
	s_or_b64 exec, exec, s[12:13]
	s_and_saveexec_b64 s[12:13], s[16:17]
	s_cbranch_execz .LBB0_562
	v_mov_b32_e32 v1, 1
.LBB0_562:
	s_or_b64 exec, exec, s[12:13]
	s_mov_b64 s[12:13], exec
	v_mbcnt_lo_u32_b32 v1, s12, 0
	v_mbcnt_hi_u32_b32 v1, s13, v1
	v_cmp_eq_u32_e32 vcc, 0, v1
	s_waitcnt vmcnt(0)
	s_and_saveexec_b64 s[14:15], vcc
	s_cbranch_execz .LBB0_564
	s_bcnt1_i32_b64 s0, s[12:13]
	v_mov_b32_e32 v1, 0x2000
	v_mov_b32_e32 v2, s0

; __device__ __forceinline__ unsigned xb_ld(unsigned* p)              { return __hip_atomic_load(p, __ATOMIC_RELAXED, __HIP_MEMORY_SCOPE_AGENT); }
; __device__ __forceinline__ unsigned xb_add(unsigned* p, unsigned v) { return __hip_atomic_fetch_add(p, v, __ATOMIC_RELAXED, __HIP_MEMORY_SCOPE_AGENT); }
; #define XB_SPIN(cond, bar) do { unsigned _sp = 0; while (cond) { __builtin_amdgcn_s_sleep(1); \
;     if ((++_sp & 255u) == 0u) { if (xb_ld(&(bar)[XB_TMO])) break; if (_sp > XB_SPIN_CAP) { atomicAdd(&(bar)[XB_TMO], 1u); break; } } } } while (0)
; __device__ __forceinline__ void xcd_barrier(const XcdBarrier& b) {
;     ...
;             if (og + 1u == (tg + 1u) * nx) xb_add(&bar[XB_TOPGEN], 1u);
;             else XB_SPIN(xb_ld(&bar[XB_TOPGEN]) == tg, bar);
;             __builtin_amdgcn_fence(__ATOMIC_ACQUIRE, "agent");
;             xb_add(&bar[XB_XGEN(b.x)], 1u);
.LBB0_705:
	s_or_b64 exec, exec, s[12:13]
	s_and_saveexec_b64 s[12:13], s[16:17]
	s_cbranch_execz .LBB0_707
	v_mov_b32_e32 v1, 1
.LBB0_707:
	s_or_b64 exec, exec, s[12:13]
	s_mov_b64 s[12:13], exec
	v_mbcnt_lo_u32_b32 v1, s12, 0
	v_mbcnt_hi_u32_b32 v1, s13, v1
	v_cmp_eq_u32_e32 vcc, 0, v1
	s_waitcnt vmcnt(0)
	s_and_saveexec_b64 s[14:15], vcc
	s_cbranch_execz .LBB0_709
	s_bcnt1_i32_b64 s0, s[12:13]
	v_mov_b32_e32 v1, 0x2000
	v_mov_b32_e32 v2, s0

; __device__ __forceinline__ unsigned xb_ld(unsigned* p)              { return __hip_atomic_load(p, __ATOMIC_RELAXED, __HIP_MEMORY_SCOPE_AGENT); }
; #define XB_SPIN(cond, bar) do { unsigned _sp = 0; while (cond) { __builtin_amdgcn_s_sleep(1); \
;     if ((++_sp & 255u) == 0u) { if (xb_ld(&(bar)[XB_TMO])) break; if (_sp > XB_SPIN_CAP) { atomicAdd(&(bar)[XB_TMO], 1u); break; } } } } while (0)
; __device__ __forceinline__ void xcd_barrier(const XcdBarrier& b) {
;     ...
;             XB_SPIN(xb_ld(&bar[XB_XGEN(b.x)]) == gen, bar);
.LBB0_785:
	global_load_dword v3, v1, s[18:19] sc1
	s_add_i32 s0, s0, 1
	s_mov_b64 s[46:47], -1
	s_waitcnt vmcnt(0)
	v_cmp_ge_u32_e32 vcc, v3, v20
	s_orn2_b64 s[44:45], vcc, exec
	s_branch .LBB0_780

; __device__ __forceinline__ unsigned xb_ld(unsigned* p)              { return __hip_atomic_load(p, __ATOMIC_RELAXED, __HIP_MEMORY_SCOPE_AGENT); }
; #define XB_SPIN(cond, bar) do { unsigned _sp = 0; while (cond) { __builtin_amdgcn_s_sleep(1); \
;     if ((++_sp & 255u) == 0u) { if (xb_ld(&(bar)[XB_TMO])) break; if (_sp > XB_SPIN_CAP) { atomicAdd(&(bar)[XB_TMO], 1u); break; } } } } while (0)
; __device__ __forceinline__ void xcd_barrier(const XcdBarrier& b) {
;     ...
;             else XB_SPIN(xb_ld(&bar[XB_TOPGEN]) == tg, bar);
.LBB0_802:
	global_load_dword v2, v1, s[14:15] sc1
	s_add_i32 s0, s0, 1
	s_mov_b64 s[44:45], -1
	s_waitcnt vmcnt(0)
	v_cmp_ge_u32_e32 vcc, v2, v20
	s_orn2_b64 s[48:49], vcc, exec
	s_branch .LBB0_797

; __device__ __forceinline__ unsigned xb_ld(unsigned* p)              { return __hip_atomic_load(p, __ATOMIC_RELAXED, __HIP_MEMORY_SCOPE_AGENT); }
; __device__ __forceinline__ unsigned xb_add(unsigned* p, unsigned v) { return __hip_atomic_fetch_add(p, v, __ATOMIC_RELAXED, __HIP_MEMORY_SCOPE_AGENT); }
; #define XB_SPIN(cond, bar) do { unsigned _sp = 0; while (cond) { __builtin_amdgcn_s_sleep(1); \
;     if ((++_sp & 255u) == 0u) { if (xb_ld(&(bar)[XB_TMO])) break; if (_sp > XB_SPIN_CAP) { atomicAdd(&(bar)[XB_TMO], 1u); break; } } } } while (0)
; __device__ __forceinline__ void xcd_barrier(const XcdBarrier& b) {
;     ...
;             if (og + 1u == (tg + 1u) * nx) xb_add(&bar[XB_TOPGEN], 1u);
;             else XB_SPIN(xb_ld(&bar[XB_TOPGEN]) == tg, bar);
;             __builtin_amdgcn_fence(__ATOMIC_ACQUIRE, "agent");
;             xb_add(&bar[XB_XGEN(b.x)], 1u);
.LBB0_806:
	s_or_b64 exec, exec, s[12:13]
	s_and_saveexec_b64 s[12:13], s[16:17]
	s_cbranch_execz .LBB0_808
	v_mov_b32_e32 v1, 1
.LBB0_808:
	s_or_b64 exec, exec, s[12:13]
	s_mov_b64 s[12:13], exec
	v_mbcnt_lo_u32_b32 v1, s12, 0
	v_mbcnt_hi_u32_b32 v1, s13, v1
	v_cmp_eq_u32_e32 vcc, 0, v1
	s_waitcnt vmcnt(0)
	s_and_saveexec_b64 s[14:15], vcc
	s_cbranch_execz .LBB0_810
	s_bcnt1_i32_b64 s0, s[12:13]
	v_mov_b32_e32 v1, 0x2000
	v_mov_b32_e32 v2, s0

; __device__ __forceinline__ unsigned xb_ld(unsigned* p)              { return __hip_atomic_load(p, __ATOMIC_RELAXED, __HIP_MEMORY_SCOPE_AGENT); }
; __device__ __forceinline__ unsigned xb_add(unsigned* p, unsigned v) { return __hip_atomic_fetch_add(p, v, __ATOMIC_RELAXED, __HIP_MEMORY_SCOPE_AGENT); }
; #define XB_SPIN(cond, bar) do { unsigned _sp = 0; while (cond) { __builtin_amdgcn_s_sleep(1); \
;     if ((++_sp & 255u) == 0u) { if (xb_ld(&(bar)[XB_TMO])) break; if (_sp > XB_SPIN_CAP) { atomicAdd(&(bar)[XB_TMO], 1u); break; } } } } while (0)
; __device__ __forceinline__ void xcd_barrier(const XcdBarrier& b) {
;     ...
;             if (og + 1u == (tg + 1u) * nx) xb_add(&bar[XB_TOPGEN], 1u);
;             else XB_SPIN(xb_ld(&bar[XB_TOPGEN]) == tg, bar);
;             __builtin_amdgcn_fence(__ATOMIC_ACQUIRE, "agent");
;             xb_add(&bar[XB_XGEN(b.x)], 1u);
.LBB0_864:
	s_or_b64 exec, exec, s[12:13]
	s_and_saveexec_b64 s[12:13], s[16:17]
	s_cbranch_execz .LBB0_866
	v_mov_b32_e32 v1, 1
.LBB0_866:
	s_or_b64 exec, exec, s[12:13]
	s_mov_b64 s[12:13], exec
	v_mbcnt_lo_u32_b32 v1, s12, 0
	v_mbcnt_hi_u32_b32 v1, s13, v1
	v_cmp_eq_u32_e32 vcc, 0, v1
	s_waitcnt vmcnt(0)
	s_and_saveexec_b64 s[14:15], vcc
	s_cbranch_execz .LBB0_868
	s_bcnt1_i32_b64 s0, s[12:13]
	v_mov_b32_e32 v1, 0x2000
	v_mov_b32_e32 v2, s0

; __device__ __forceinline__ unsigned xb_ld(unsigned* p)              { return __hip_atomic_load(p, __ATOMIC_RELAXED, __HIP_MEMORY_SCOPE_AGENT); }
; __device__ __forceinline__ unsigned xb_add(unsigned* p, unsigned v) { return __hip_atomic_fetch_add(p, v, __ATOMIC_RELAXED, __HIP_MEMORY_SCOPE_AGENT); }
; #define XB_SPIN(cond, bar) do { unsigned _sp = 0; while (cond) { __builtin_amdgcn_s_sleep(1); \
;     if ((++_sp & 255u) == 0u) { if (xb_ld(&(bar)[XB_TMO])) break; if (_sp > XB_SPIN_CAP) { atomicAdd(&(bar)[XB_TMO], 1u); break; } } } } while (0)
; __device__ __forceinline__ void xcd_barrier(const XcdBarrier& b) {
;     ...
;             if (og + 1u == (tg + 1u) * nx) xb_add(&bar[XB_TOPGEN], 1u);
;             else XB_SPIN(xb_ld(&bar[XB_TOPGEN]) == tg, bar);
;             __builtin_amdgcn_fence(__ATOMIC_ACQUIRE, "agent");
;             xb_add(&bar[XB_XGEN(b.x)], 1u);
.LBB0_1051:
	s_or_b64 exec, exec, s[12:13]
	s_and_saveexec_b64 s[12:13], s[16:17]
	s_cbranch_execz .LBB0_1053
	v_mov_b32_e32 v1, 1
.LBB0_1053:
	s_or_b64 exec, exec, s[12:13]
	s_mov_b64 s[12:13], exec
	v_mbcnt_lo_u32_b32 v1, s12, 0
	v_mbcnt_hi_u32_b32 v1, s13, v1
	v_cmp_eq_u32_e32 vcc, 0, v1
	s_waitcnt vmcnt(0)
	s_and_saveexec_b64 s[14:15], vcc
	s_cbranch_execz .LBB0_1055
	s_bcnt1_i32_b64 s0, s[12:13]
	v_mov_b32_e32 v1, 0x2000
	v_mov_b32_e32 v2, s0

; __device__ __forceinline__ unsigned xb_ld(unsigned* p)              { return __hip_atomic_load(p, __ATOMIC_RELAXED, __HIP_MEMORY_SCOPE_AGENT); }
; __device__ __forceinline__ unsigned xb_add(unsigned* p, unsigned v) { return __hip_atomic_fetch_add(p, v, __ATOMIC_RELAXED, __HIP_MEMORY_SCOPE_AGENT); }
; #define XB_SPIN(cond, bar) do { unsigned _sp = 0; while (cond) { __builtin_amdgcn_s_sleep(1); \
;     if ((++_sp & 255u) == 0u) { if (xb_ld(&(bar)[XB_TMO])) break; if (_sp > XB_SPIN_CAP) { atomicAdd(&(bar)[XB_TMO], 1u); break; } } } } while (0)
; __device__ __forceinline__ void xcd_barrier(const XcdBarrier& b) {
;     ...
;             if (og + 1u == (tg + 1u) * nx) xb_add(&bar[XB_TOPGEN], 1u);
;             else XB_SPIN(xb_ld(&bar[XB_TOPGEN]) == tg, bar);
;             __builtin_amdgcn_fence(__ATOMIC_ACQUIRE, "agent");
;             xb_add(&bar[XB_XGEN(b.x)], 1u);
.LBB0_1116:
	s_or_b64 exec, exec, s[12:13]
	s_and_saveexec_b64 s[12:13], s[16:17]
	s_cbranch_execz .LBB0_1118
	v_mov_b32_e32 v1, 1
.LBB0_1118:
	s_or_b64 exec, exec, s[12:13]
	s_mov_b64 s[12:13], exec
	v_mbcnt_lo_u32_b32 v1, s12, 0
	v_mbcnt_hi_u32_b32 v1, s13, v1
	v_cmp_eq_u32_e32 vcc, 0, v1
	s_waitcnt vmcnt(0)
	s_and_saveexec_b64 s[14:15], vcc
	s_cbranch_execz .LBB0_1120
	s_bcnt1_i32_b64 s0, s[12:13]
	v_mov_b32_e32 v1, 0x2000
	v_mov_b32_e32 v2, s0

; __device__ __forceinline__ unsigned xb_ld(unsigned* p)              { return __hip_atomic_load(p, __ATOMIC_RELAXED, __HIP_MEMORY_SCOPE_AGENT); }
; __device__ __forceinline__ unsigned xb_add(unsigned* p, unsigned v) { return __hip_atomic_fetch_add(p, v, __ATOMIC_RELAXED, __HIP_MEMORY_SCOPE_AGENT); }
; #define XB_SPIN(cond, bar) do { unsigned _sp = 0; while (cond) { __builtin_amdgcn_s_sleep(1); \
;     if ((++_sp & 255u) == 0u) { if (xb_ld(&(bar)[XB_TMO])) break; if (_sp > XB_SPIN_CAP) { atomicAdd(&(bar)[XB_TMO], 1u); break; } } } } while (0)
; __device__ __forceinline__ void xcd_barrier(const XcdBarrier& b) {
;     ...
;         const unsigned old = xb_add(&bar[XB_XSUB(b.x)], 1u);
;         const unsigned gen = old / nloc;
;         if (old + 1u == (gen + 1u) * nloc) {
;             __builtin_amdgcn_fence(__ATOMIC_RELEASE, "agent");
;             asm volatile("s_waitcnt vmcnt(0)" ::: "memory");
;             const unsigned og = xb_add(&bar[XB_TOP], 1u);
;             const unsigned tg = og / nx;
;             if (og + 1u == (tg + 1u) * nx) xb_add(&bar[XB_TOPGEN], 1u);
;             else XB_SPIN(xb_ld(&bar[XB_TOPGEN]) == tg, bar);
;             __builtin_amdgcn_fence(__ATOMIC_ACQUIRE, "agent");
;             xb_add(&bar[XB_XGEN(b.x)], 1u);
;             asm volatile("s_waitcnt vmcnt(0)" ::: "memory");
;         } else {
;             XB_SPIN(xb_ld(&bar[XB_XGEN(b.x)]) == gen, bar);
;             __builtin_amdgcn_fence(__ATOMIC_ACQUIRE, "agent");
.LBB0_1317:
	s_or_b64 exec, exec, s[12:13]
	v_cvt_f32_u32_e32 v5, v3
	s_waitcnt vmcnt(0)
	v_readfirstlane_b32 s2, v4
	v_sub_u32_e32 v4, 0, v3
	v_rcp_iflag_f32_e32 v5, v5
	v_add_u32_e32 v6, s2, v2
	v_mul_f32_e32 v5, 0x4f7ffffe, v5
	v_cvt_u32_f32_e32 v5, v5
	v_mul_lo_u32 v2, v4, v5
	v_mul_hi_u32 v2, v5, v2
	v_add_u32_e32 v2, v5, v2
	v_mul_hi_u32 v2, v6, v2
	v_mul_lo_u32 v4, v2, v3
	v_sub_u32_e32 v4, v6, v4
	v_add_u32_e32 v5, 1, v2
	v_cmp_ge_u32_e32 vcc, v4, v3
	s_nop 1
	v_cndmask_b32_e32 v2, v2, v5, vcc
	v_sub_u32_e32 v5, v4, v3
	v_cndmask_b32_e32 v4, v4, v5, vcc
	v_add_u32_e32 v5, 1, v2
	v_cmp_ge_u32_e32 vcc, v4, v3
	v_add_u32_e32 v4, 1, v6
	s_nop 0
	v_cndmask_b32_e32 v2, v2, v5, vcc
	v_mul_lo_u32 v5, v3, v2
	v_add_u32_e32 v3, v5, v3
	v_cmp_ne_u32_e32 vcc, v4, v3
	s_and_saveexec_b64 s[2:3], vcc
	s_xor_b64 s[10:11], exec, s[2:3]
	s_cbranch_execz .LBB0_1331
	s_waitcnt lgkmcnt(0)
	v_add_u32_e32 v20, 1, v2
	v_mul_lo_u32 v20, v20, v1
	buffer_inv sc1
	s_add_u32 s44, s26, 0xff03400
	s_addc_u32 s45, s27, 0
	v_mov_b32_e32 v1, 0
	global_load_dword v1, v1, s[44:45] sc1
	s_waitcnt vmcnt(0)
	v_cmp_lt_u32_e32 vcc, v1, v20
	s_and_saveexec_b64 s[12:13], vcc
	s_cbranch_execz .LBB0_1330
	s_add_u32 s42, s26, 0xff00200
	s_addc_u32 s43, s27, 0
	s_mov_b32 s2, 1
	s_mov_b64 s[46:47], 0
	v_mov_b32_e32 v1, 0
	s_branch .LBB0_1321

; __device__ __forceinline__ unsigned xb_ld(unsigned* p)              { return __hip_atomic_load(p, __ATOMIC_RELAXED, __HIP_MEMORY_SCOPE_AGENT); }
; #define XB_SPIN(cond, bar) do { unsigned _sp = 0; while (cond) { __builtin_amdgcn_s_sleep(1); \
;     if ((++_sp & 255u) == 0u) { if (xb_ld(&(bar)[XB_TMO])) break; if (_sp > XB_SPIN_CAP) { atomicAdd(&(bar)[XB_TMO], 1u); break; } } } } while (0)
; __device__ __forceinline__ void xcd_barrier(const XcdBarrier& b) {
;     ...
;             XB_SPIN(xb_ld(&bar[XB_XGEN(b.x)]) == gen, bar);
.LBB0_1325:
	global_load_dword v3, v1, s[44:45] sc1
	s_add_i32 s2, s2, 1
	s_mov_b64 s[52:53], -1
	s_waitcnt vmcnt(0)
	v_cmp_ge_u32_e32 vcc, v3, v20
	s_orn2_b64 s[50:51], vcc, exec
	s_branch .LBB0_1320

; __device__ __forceinline__ unsigned xb_ld(unsigned* p)              { return __hip_atomic_load(p, __ATOMIC_RELAXED, __HIP_MEMORY_SCOPE_AGENT); }
; __device__ __forceinline__ unsigned xb_add(unsigned* p, unsigned v) { return __hip_atomic_fetch_add(p, v, __ATOMIC_RELAXED, __HIP_MEMORY_SCOPE_AGENT); }
; #define XB_SPIN(cond, bar) do { unsigned _sp = 0; while (cond) { __builtin_amdgcn_s_sleep(1); \
;     if ((++_sp & 255u) == 0u) { if (xb_ld(&(bar)[XB_TMO])) break; if (_sp > XB_SPIN_CAP) { atomicAdd(&(bar)[XB_TMO], 1u); break; } } } } while (0)
; __device__ __forceinline__ void xcd_barrier(const XcdBarrier& b) {
;     ...
;             const unsigned og = xb_add(&bar[XB_TOP], 1u);
;             const unsigned tg = og / nx;
;             if (og + 1u == (tg + 1u) * nx) xb_add(&bar[XB_TOPGEN], 1u);
;             else XB_SPIN(xb_ld(&bar[XB_TOPGEN]) == tg, bar);
.LBB0_1334:
	s_or_b64 exec, exec, s[12:13]
	v_cvt_f32_u32_e32 v4, v1
	s_waitcnt vmcnt(0)
	v_readfirstlane_b32 s2, v3
	s_add_u32 s12, s26, 0xff03400
	s_addc_u32 s13, s27, 0
	v_rcp_iflag_f32_e32 v4, v4
	v_add_u32_e32 v2, s2, v2
	v_add_u32_e32 v5, 1, v2
	s_mov_b64 s[42:43], -1
	v_mul_f32_e32 v3, 0x4f7ffffe, v4
	v_cvt_u32_f32_e32 v3, v3
	v_sub_u32_e32 v4, 0, v1
	v_mul_lo_u32 v4, v4, v3
	v_mul_hi_u32 v4, v3, v4
	v_add_u32_e32 v3, v3, v4
	v_mul_hi_u32 v3, v2, v3
	v_mul_lo_u32 v4, v3, v1
	v_sub_u32_e32 v2, v2, v4
	v_add_u32_e32 v6, 1, v3
	v_cmp_ge_u32_e32 vcc, v2, v1
	v_sub_u32_e32 v4, v2, v1
	s_nop 0
	v_cndmask_b32_e32 v3, v3, v6, vcc
	v_cndmask_b32_e32 v2, v2, v4, vcc
	v_add_u32_e32 v4, 1, v3
	v_cmp_ge_u32_e32 vcc, v2, v1
	s_nop 1
	v_cndmask_b32_e32 v4, v3, v4, vcc
	v_mul_lo_u32 v2, v1, v4
	v_add_u32_e32 v1, v2, v1
	v_cmp_ne_u32_e32 vcc, v5, v1
	v_mov_b64_e32 v[2:3], s[12:13]
	s_and_saveexec_b64 s[10:11], vcc
	s_cbranch_execz .LBB0_1346
	v_mov_b32_e32 v20, v1
	v_mov_b32_e32 v1, 0
	global_load_dword v2, v1, s[12:13] sc1
	s_mov_b64 s[46:47], 0
	s_waitcnt vmcnt(0)
	v_cmp_lt_u32_e32 vcc, v2, v20
	s_and_saveexec_b64 s[44:45], vcc
	s_cbranch_execz .LBB0_1345
	s_add_u32 s42, s26, 0xff00200
	s_addc_u32 s43, s27, 0
	s_mov_b32 s2, 1
	s_branch .LBB0_1338

; __device__ __forceinline__ unsigned xb_ld(unsigned* p)              { return __hip_atomic_load(p, __ATOMIC_RELAXED, __HIP_MEMORY_SCOPE_AGENT); }
; #define XB_SPIN(cond, bar) do { unsigned _sp = 0; while (cond) { __builtin_amdgcn_s_sleep(1); \
;     if ((++_sp & 255u) == 0u) { if (xb_ld(&(bar)[XB_TMO])) break; if (_sp > XB_SPIN_CAP) { atomicAdd(&(bar)[XB_TMO], 1u); break; } } } } while (0)
; __device__ __forceinline__ void xcd_barrier(const XcdBarrier& b) {
;     ...
;             else XB_SPIN(xb_ld(&bar[XB_TOPGEN]) == tg, bar);
.LBB0_1342:
	global_load_dword v2, v1, s[12:13] sc1
	s_add_i32 s2, s2, 1
	s_mov_b64 s[50:51], -1
	s_waitcnt vmcnt(0)
	v_cmp_ge_u32_e32 vcc, v2, v20
	s_orn2_b64 s[54:55], vcc, exec
	s_branch .LBB0_1337

; __device__ __forceinline__ unsigned xb_ld(unsigned* p)              { return __hip_atomic_load(p, __ATOMIC_RELAXED, __HIP_MEMORY_SCOPE_AGENT); }
; __device__ __forceinline__ unsigned xb_add(unsigned* p, unsigned v) { return __hip_atomic_fetch_add(p, v, __ATOMIC_RELAXED, __HIP_MEMORY_SCOPE_AGENT); }
; #define XB_SPIN(cond, bar) do { unsigned _sp = 0; while (cond) { __builtin_amdgcn_s_sleep(1); \
;     if ((++_sp & 255u) == 0u) { if (xb_ld(&(bar)[XB_TMO])) break; if (_sp > XB_SPIN_CAP) { atomicAdd(&(bar)[XB_TMO], 1u); break; } } } } while (0)
; __device__ __forceinline__ void xcd_barrier(const XcdBarrier& b) {
;     ...
;             if (og + 1u == (tg + 1u) * nx) xb_add(&bar[XB_TOPGEN], 1u);
;             else XB_SPIN(xb_ld(&bar[XB_TOPGEN]) == tg, bar);
;             __builtin_amdgcn_fence(__ATOMIC_ACQUIRE, "agent");
;             xb_add(&bar[XB_XGEN(b.x)], 1u);
.LBB0_1346:
	s_or_b64 exec, exec, s[10:11]
	s_and_saveexec_b64 s[10:11], s[42:43]
	s_cbranch_execz .LBB0_1348
	v_mov_b32_e32 v1, 1
.LBB0_1348:
	s_or_b64 exec, exec, s[10:11]
	s_mov_b64 s[10:11], exec
	v_mbcnt_lo_u32_b32 v1, s10, 0
	v_mbcnt_hi_u32_b32 v1, s11, v1
	v_cmp_eq_u32_e32 vcc, 0, v1
	s_waitcnt vmcnt(0)
	s_and_saveexec_b64 s[12:13], vcc
	s_cbranch_execz .LBB0_1350
	s_bcnt1_i32_b64 s2, s[10:11]
	v_mov_b32_e32 v1, 0x2000
	v_mov_b32_e32 v2, s2

; __device__ __forceinline__ unsigned xb_ld(unsigned* p)              { return __hip_atomic_load(p, __ATOMIC_RELAXED, __HIP_MEMORY_SCOPE_AGENT); }
; __device__ __forceinline__ unsigned xb_add(unsigned* p, unsigned v) { return __hip_atomic_fetch_add(p, v, __ATOMIC_RELAXED, __HIP_MEMORY_SCOPE_AGENT); }
; #define XB_SPIN(cond, bar) do { unsigned _sp = 0; while (cond) { __builtin_amdgcn_s_sleep(1); \
;     if ((++_sp & 255u) == 0u) { if (xb_ld(&(bar)[XB_TMO])) break; if (_sp > XB_SPIN_CAP) { atomicAdd(&(bar)[XB_TMO], 1u); break; } } } } while (0)
; __device__ __forceinline__ void xcd_barrier(const XcdBarrier& b) {
;     ...
;         const unsigned old = xb_add(&bar[XB_XSUB(b.x)], 1u);
;         const unsigned gen = old / nloc;
;         if (old + 1u == (gen + 1u) * nloc) {
;             __builtin_amdgcn_fence(__ATOMIC_RELEASE, "agent");
;             asm volatile("s_waitcnt vmcnt(0)" ::: "memory");
;             const unsigned og = xb_add(&bar[XB_TOP], 1u);
;             const unsigned tg = og / nx;
;             if (og + 1u == (tg + 1u) * nx) xb_add(&bar[XB_TOPGEN], 1u);
;             else XB_SPIN(xb_ld(&bar[XB_TOPGEN]) == tg, bar);
;             __builtin_amdgcn_fence(__ATOMIC_ACQUIRE, "agent");
;             xb_add(&bar[XB_XGEN(b.x)], 1u);
;             asm volatile("s_waitcnt vmcnt(0)" ::: "memory");
;         } else {
;             XB_SPIN(xb_ld(&bar[XB_XGEN(b.x)]) == gen, bar);
;             __builtin_amdgcn_fence(__ATOMIC_ACQUIRE, "agent");
.LBB0_1552:
	s_or_b64 exec, exec, s[12:13]
	v_cvt_f32_u32_e32 v5, v3
	s_waitcnt vmcnt(0)
	v_readfirstlane_b32 s2, v4
	v_sub_u32_e32 v4, 0, v3
	v_rcp_iflag_f32_e32 v5, v5
	v_add_u32_e32 v6, s2, v2
	v_mul_f32_e32 v5, 0x4f7ffffe, v5
	v_cvt_u32_f32_e32 v5, v5
	v_mul_lo_u32 v2, v4, v5
	v_mul_hi_u32 v2, v5, v2
	v_add_u32_e32 v2, v5, v2
	v_mul_hi_u32 v2, v6, v2
	v_mul_lo_u32 v4, v2, v3
	v_sub_u32_e32 v4, v6, v4
	v_add_u32_e32 v5, 1, v2
	v_cmp_ge_u32_e32 vcc, v4, v3
	s_nop 1
	v_cndmask_b32_e32 v2, v2, v5, vcc
	v_sub_u32_e32 v5, v4, v3
	v_cndmask_b32_e32 v4, v4, v5, vcc
	v_add_u32_e32 v5, 1, v2
	v_cmp_ge_u32_e32 vcc, v4, v3
	v_add_u32_e32 v4, 1, v6
	s_nop 0
	v_cndmask_b32_e32 v2, v2, v5, vcc
	v_mul_lo_u32 v5, v3, v2
	v_add_u32_e32 v3, v5, v3
	v_cmp_ne_u32_e32 vcc, v4, v3
	s_and_saveexec_b64 s[2:3], vcc
	s_xor_b64 s[10:11], exec, s[2:3]
	s_cbranch_execz .LBB0_1566
	s_waitcnt lgkmcnt(0)
	v_add_u32_e32 v20, 1, v2
	v_mul_lo_u32 v20, v20, v1
	buffer_inv sc1
	s_add_u32 s16, s26, 0xff03400
	s_addc_u32 s17, s27, 0
	v_mov_b32_e32 v1, 0
	global_load_dword v1, v1, s[16:17] sc1
	s_waitcnt vmcnt(0)
	v_cmp_lt_u32_e32 vcc, v1, v20
	s_and_saveexec_b64 s[12:13], vcc
	s_cbranch_execz .LBB0_1565
	s_add_u32 s14, s26, 0xff00200
	s_addc_u32 s15, s27, 0
	s_mov_b32 s2, 1
	s_mov_b64 s[18:19], 0
	v_mov_b32_e32 v1, 0
	s_branch .LBB0_1556

; __device__ __forceinline__ unsigned xb_ld(unsigned* p)              { return __hip_atomic_load(p, __ATOMIC_RELAXED, __HIP_MEMORY_SCOPE_AGENT); }
; #define XB_SPIN(cond, bar) do { unsigned _sp = 0; while (cond) { __builtin_amdgcn_s_sleep(1); \
;     if ((++_sp & 255u) == 0u) { if (xb_ld(&(bar)[XB_TMO])) break; if (_sp > XB_SPIN_CAP) { atomicAdd(&(bar)[XB_TMO], 1u); break; } } } } while (0)
; __device__ __forceinline__ void xcd_barrier(const XcdBarrier& b) {
;     ...
;             XB_SPIN(xb_ld(&bar[XB_XGEN(b.x)]) == gen, bar);
.LBB0_1560:
	global_load_dword v3, v1, s[16:17] sc1
	s_add_i32 s2, s2, 1
	s_mov_b64 s[42:43], -1
	s_waitcnt vmcnt(0)
	v_cmp_ge_u32_e32 vcc, v3, v20
	s_orn2_b64 s[38:39], vcc, exec
	s_branch .LBB0_1555

; __device__ __forceinline__ unsigned xb_ld(unsigned* p)              { return __hip_atomic_load(p, __ATOMIC_RELAXED, __HIP_MEMORY_SCOPE_AGENT); }
; __device__ __forceinline__ unsigned xb_add(unsigned* p, unsigned v) { return __hip_atomic_fetch_add(p, v, __ATOMIC_RELAXED, __HIP_MEMORY_SCOPE_AGENT); }
; #define XB_SPIN(cond, bar) do { unsigned _sp = 0; while (cond) { __builtin_amdgcn_s_sleep(1); \
;     if ((++_sp & 255u) == 0u) { if (xb_ld(&(bar)[XB_TMO])) break; if (_sp > XB_SPIN_CAP) { atomicAdd(&(bar)[XB_TMO], 1u); break; } } } } while (0)
; __device__ __forceinline__ void xcd_barrier(const XcdBarrier& b) {
;     ...
;             const unsigned og = xb_add(&bar[XB_TOP], 1u);
;             const unsigned tg = og / nx;
;             if (og + 1u == (tg + 1u) * nx) xb_add(&bar[XB_TOPGEN], 1u);
;             else XB_SPIN(xb_ld(&bar[XB_TOPGEN]) == tg, bar);
.LBB0_1569:
	s_or_b64 exec, exec, s[12:13]
	v_cvt_f32_u32_e32 v4, v1
	s_waitcnt vmcnt(0)
	v_readfirstlane_b32 s2, v3
	s_add_u32 s12, s26, 0xff03400
	s_addc_u32 s13, s27, 0
	v_rcp_iflag_f32_e32 v4, v4
	v_add_u32_e32 v2, s2, v2
	v_add_u32_e32 v5, 1, v2
	s_mov_b64 s[14:15], -1
	v_mul_f32_e32 v3, 0x4f7ffffe, v4
	v_cvt_u32_f32_e32 v3, v3
	v_sub_u32_e32 v4, 0, v1
	v_mul_lo_u32 v4, v4, v3
	v_mul_hi_u32 v4, v3, v4
	v_add_u32_e32 v3, v3, v4
	v_mul_hi_u32 v3, v2, v3
	v_mul_lo_u32 v4, v3, v1
	v_sub_u32_e32 v2, v2, v4
	v_add_u32_e32 v6, 1, v3
	v_cmp_ge_u32_e32 vcc, v2, v1
	v_sub_u32_e32 v4, v2, v1
	s_nop 0
	v_cndmask_b32_e32 v3, v3, v6, vcc
	v_cndmask_b32_e32 v2, v2, v4, vcc
	v_add_u32_e32 v4, 1, v3
	v_cmp_ge_u32_e32 vcc, v2, v1
	s_nop 1
	v_cndmask_b32_e32 v4, v3, v4, vcc
	v_mul_lo_u32 v2, v1, v4
	v_add_u32_e32 v1, v2, v1
	v_cmp_ne_u32_e32 vcc, v5, v1
	v_mov_b64_e32 v[2:3], s[12:13]
	s_and_saveexec_b64 s[10:11], vcc
	s_cbranch_execz .LBB0_1581
	v_mov_b32_e32 v20, v1
	v_mov_b32_e32 v1, 0
	global_load_dword v2, v1, s[12:13] sc1
	s_mov_b64 s[18:19], 0
	s_waitcnt vmcnt(0)
	v_cmp_lt_u32_e32 vcc, v2, v20
	s_and_saveexec_b64 s[16:17], vcc
	s_cbranch_execz .LBB0_1580
	s_add_u32 s14, s26, 0xff00200
	s_addc_u32 s15, s27, 0
	s_mov_b32 s2, 1
	s_branch .LBB0_1573

; __device__ __forceinline__ unsigned xb_ld(unsigned* p)              { return __hip_atomic_load(p, __ATOMIC_RELAXED, __HIP_MEMORY_SCOPE_AGENT); }
; #define XB_SPIN(cond, bar) do { unsigned _sp = 0; while (cond) { __builtin_amdgcn_s_sleep(1); \
;     if ((++_sp & 255u) == 0u) { if (xb_ld(&(bar)[XB_TMO])) break; if (_sp > XB_SPIN_CAP) { atomicAdd(&(bar)[XB_TMO], 1u); break; } } } } while (0)
; __device__ __forceinline__ void xcd_barrier(const XcdBarrier& b) {
;     ...
;             else XB_SPIN(xb_ld(&bar[XB_TOPGEN]) == tg, bar);
.LBB0_1577:
	global_load_dword v2, v1, s[12:13] sc1
	s_add_i32 s2, s2, 1
	s_mov_b64 s[38:39], -1
	s_waitcnt vmcnt(0)
	v_cmp_ge_u32_e32 vcc, v2, v20
	s_orn2_b64 s[44:45], vcc, exec
	s_branch .LBB0_1572

; __device__ __forceinline__ unsigned xb_ld(unsigned* p)              { return __hip_atomic_load(p, __ATOMIC_RELAXED, __HIP_MEMORY_SCOPE_AGENT); }
; __device__ __forceinline__ unsigned xb_add(unsigned* p, unsigned v) { return __hip_atomic_fetch_add(p, v, __ATOMIC_RELAXED, __HIP_MEMORY_SCOPE_AGENT); }
; #define XB_SPIN(cond, bar) do { unsigned _sp = 0; while (cond) { __builtin_amdgcn_s_sleep(1); \
;     if ((++_sp & 255u) == 0u) { if (xb_ld(&(bar)[XB_TMO])) break; if (_sp > XB_SPIN_CAP) { atomicAdd(&(bar)[XB_TMO], 1u); break; } } } } while (0)
; __device__ __forceinline__ void xcd_barrier(const XcdBarrier& b) {
;     ...
;             if (og + 1u == (tg + 1u) * nx) xb_add(&bar[XB_TOPGEN], 1u);
;             else XB_SPIN(xb_ld(&bar[XB_TOPGEN]) == tg, bar);
;             __builtin_amdgcn_fence(__ATOMIC_ACQUIRE, "agent");
;             xb_add(&bar[XB_XGEN(b.x)], 1u);
.LBB0_1581:
	s_or_b64 exec, exec, s[10:11]
	s_and_saveexec_b64 s[10:11], s[14:15]
	s_cbranch_execz .LBB0_1583
	v_mov_b32_e32 v1, 1
.LBB0_1583:
	s_or_b64 exec, exec, s[10:11]
	s_mov_b64 s[10:11], exec
	v_mbcnt_lo_u32_b32 v1, s10, 0
	v_mbcnt_hi_u32_b32 v1, s11, v1
	v_cmp_eq_u32_e32 vcc, 0, v1
	s_waitcnt vmcnt(0)
	s_and_saveexec_b64 s[12:13], vcc
	s_cbranch_execz .LBB0_1585
	s_bcnt1_i32_b64 s2, s[10:11]
	v_mov_b32_e32 v1, 0x2000
	v_mov_b32_e32 v2, s2

; __device__ __forceinline__ unsigned xb_ld(unsigned* p)              { return __hip_atomic_load(p, __ATOMIC_RELAXED, __HIP_MEMORY_SCOPE_AGENT); }
; #define XB_SPIN(cond, bar) do { unsigned _sp = 0; while (cond) { __builtin_amdgcn_s_sleep(1); \
;     if ((++_sp & 255u) == 0u) { if (xb_ld(&(bar)[XB_TMO])) break; if (_sp > XB_SPIN_CAP) { atomicAdd(&(bar)[XB_TMO], 1u); break; } } } } while (0)
; __device__ __forceinline__ void xcd_barrier(const XcdBarrier& b) {
;     ...
;             XB_SPIN(xb_ld(&bar[XB_XGEN(b.x)]) == gen, bar);
.LBB0_1657:
	global_load_dword v3, v1, s[16:17] sc1
	s_add_i32 s2, s2, 1
	s_mov_b64 s[40:41], -1
	s_waitcnt vmcnt(0)
	v_cmp_ge_u32_e32 vcc, v3, v20
	s_orn2_b64 s[38:39], vcc, exec
	s_branch .LBB0_1652

; __device__ __forceinline__ unsigned xb_ld(unsigned* p)              { return __hip_atomic_load(p, __ATOMIC_RELAXED, __HIP_MEMORY_SCOPE_AGENT); }
; #define XB_SPIN(cond, bar) do { unsigned _sp = 0; while (cond) { __builtin_amdgcn_s_sleep(1); \
;     if ((++_sp & 255u) == 0u) { if (xb_ld(&(bar)[XB_TMO])) break; if (_sp > XB_SPIN_CAP) { atomicAdd(&(bar)[XB_TMO], 1u); break; } } } } while (0)
; __device__ __forceinline__ void xcd_barrier(const XcdBarrier& b) {
;     ...
;             else XB_SPIN(xb_ld(&bar[XB_TOPGEN]) == tg, bar);
.LBB0_1674:
	global_load_dword v2, v1, s[12:13] sc1
	s_add_i32 s2, s2, 1
	s_mov_b64 s[38:39], -1
	s_waitcnt vmcnt(0)
	v_cmp_ge_u32_e32 vcc, v2, v20
	s_orn2_b64 s[42:43], vcc, exec
	s_branch .LBB0_1669

; __device__ __forceinline__ unsigned xb_ld(unsigned* p)              { return __hip_atomic_load(p, __ATOMIC_RELAXED, __HIP_MEMORY_SCOPE_AGENT); }
; __device__ __forceinline__ unsigned xb_add(unsigned* p, unsigned v) { return __hip_atomic_fetch_add(p, v, __ATOMIC_RELAXED, __HIP_MEMORY_SCOPE_AGENT); }
; #define XB_SPIN(cond, bar) do { unsigned _sp = 0; while (cond) { __builtin_amdgcn_s_sleep(1); \
;     if ((++_sp & 255u) == 0u) { if (xb_ld(&(bar)[XB_TMO])) break; if (_sp > XB_SPIN_CAP) { atomicAdd(&(bar)[XB_TMO], 1u); break; } } } } while (0)
; __device__ __forceinline__ void xcd_barrier(const XcdBarrier& b) {
;     ...
;             if (og + 1u == (tg + 1u) * nx) xb_add(&bar[XB_TOPGEN], 1u);
;             else XB_SPIN(xb_ld(&bar[XB_TOPGEN]) == tg, bar);
;             __builtin_amdgcn_fence(__ATOMIC_ACQUIRE, "agent");
;             xb_add(&bar[XB_XGEN(b.x)], 1u);
.LBB0_1678:
	s_or_b64 exec, exec, s[10:11]
	s_and_saveexec_b64 s[10:11], s[14:15]
	s_cbranch_execz .LBB0_1680
	v_mov_b32_e32 v1, 1
.LBB0_1680:
	s_or_b64 exec, exec, s[10:11]
	s_mov_b64 s[10:11], exec
	v_mbcnt_lo_u32_b32 v1, s10, 0
	v_mbcnt_hi_u32_b32 v1, s11, v1
	v_cmp_eq_u32_e32 vcc, 0, v1
	s_waitcnt vmcnt(0)
	s_and_saveexec_b64 s[12:13], vcc
	s_cbranch_execz .LBB0_1682
	s_bcnt1_i32_b64 s2, s[10:11]
	v_mov_b32_e32 v1, 0x2000
	v_mov_b32_e32 v2, s2

; __device__ __forceinline__ unsigned xb_ld(unsigned* p)              { return __hip_atomic_load(p, __ATOMIC_RELAXED, __HIP_MEMORY_SCOPE_AGENT); }
; __device__ __forceinline__ unsigned xb_add(unsigned* p, unsigned v) { return __hip_atomic_fetch_add(p, v, __ATOMIC_RELAXED, __HIP_MEMORY_SCOPE_AGENT); }
; #define XB_SPIN(cond, bar) do { unsigned _sp = 0; while (cond) { __builtin_amdgcn_s_sleep(1); \
;     if ((++_sp & 255u) == 0u) { if (xb_ld(&(bar)[XB_TMO])) break; if (_sp > XB_SPIN_CAP) { atomicAdd(&(bar)[XB_TMO], 1u); break; } } } } while (0)
; __device__ __forceinline__ void xcd_barrier(const XcdBarrier& b) {
;     ...
;         const unsigned old = xb_add(&bar[XB_XSUB(b.x)], 1u);
;         const unsigned gen = old / nloc;
;         if (old + 1u == (gen + 1u) * nloc) {
;             __builtin_amdgcn_fence(__ATOMIC_RELEASE, "agent");
;             asm volatile("s_waitcnt vmcnt(0)" ::: "memory");
;             const unsigned og = xb_add(&bar[XB_TOP], 1u);
;             const unsigned tg = og / nx;
;             if (og + 1u == (tg + 1u) * nx) xb_add(&bar[XB_TOPGEN], 1u);
;             else XB_SPIN(xb_ld(&bar[XB_TOPGEN]) == tg, bar);
;             __builtin_amdgcn_fence(__ATOMIC_ACQUIRE, "agent");
;             xb_add(&bar[XB_XGEN(b.x)], 1u);
;             asm volatile("s_waitcnt vmcnt(0)" ::: "memory");
;         } else {
;             XB_SPIN(xb_ld(&bar[XB_XGEN(b.x)]) == gen, bar);
;             __builtin_amdgcn_fence(__ATOMIC_ACQUIRE, "agent");
.LBB0_1814:
	s_or_b64 exec, exec, s[10:11]
	v_cvt_f32_u32_e32 v4, v2
	s_waitcnt vmcnt(0)
	v_readfirstlane_b32 s2, v3
	v_sub_u32_e32 v3, 0, v2
	v_rcp_iflag_f32_e32 v4, v4
	v_add_u32_e32 v5, s2, v1
	v_mul_f32_e32 v4, 0x4f7ffffe, v4
	v_cvt_u32_f32_e32 v4, v4
	v_mul_lo_u32 v1, v3, v4
	v_mul_hi_u32 v1, v4, v1
	v_add_u32_e32 v1, v4, v1
	v_mul_hi_u32 v1, v5, v1
	v_mul_lo_u32 v3, v1, v2
	v_sub_u32_e32 v3, v5, v3
	v_add_u32_e32 v4, 1, v1
	v_cmp_ge_u32_e32 vcc, v3, v2
	s_nop 1
	v_cndmask_b32_e32 v1, v1, v4, vcc
	v_sub_u32_e32 v4, v3, v2
	v_cndmask_b32_e32 v3, v3, v4, vcc
	v_add_u32_e32 v4, 1, v1
	v_cmp_ge_u32_e32 vcc, v3, v2
	v_add_u32_e32 v3, 1, v5
	s_nop 0
	v_cndmask_b32_e32 v1, v1, v4, vcc
	v_mul_lo_u32 v4, v2, v1
	v_add_u32_e32 v2, v4, v2
	v_cmp_ne_u32_e32 vcc, v3, v2
	s_and_saveexec_b64 s[2:3], vcc
	s_xor_b64 s[8:9], exec, s[2:3]
	s_cbranch_execz .LBB0_1828
	s_waitcnt lgkmcnt(0)
	v_add_u32_e32 v20, 1, v1
	v_mul_lo_u32 v20, v20, v0
	buffer_inv sc1
	s_add_u32 s16, s26, 0xff03400
	s_addc_u32 s17, s27, 0
	v_mov_b32_e32 v0, 0
	global_load_dword v0, v0, s[16:17] sc1
	s_waitcnt vmcnt(0)
	v_cmp_lt_u32_e32 vcc, v0, v20
	s_and_saveexec_b64 s[10:11], vcc
	s_cbranch_execz .LBB0_1827
	s_add_u32 s14, s26, 0xff00200
	s_addc_u32 s15, s27, 0
	s_mov_b32 s2, 1
	s_mov_b64 s[18:19], 0
	v_mov_b32_e32 v0, 0
	s_branch .LBB0_1818

; __device__ __forceinline__ unsigned xb_ld(unsigned* p)              { return __hip_atomic_load(p, __ATOMIC_RELAXED, __HIP_MEMORY_SCOPE_AGENT); }
; #define XB_SPIN(cond, bar) do { unsigned _sp = 0; while (cond) { __builtin_amdgcn_s_sleep(1); \
;     if ((++_sp & 255u) == 0u) { if (xb_ld(&(bar)[XB_TMO])) break; if (_sp > XB_SPIN_CAP) { atomicAdd(&(bar)[XB_TMO], 1u); break; } } } } while (0)
; __device__ __forceinline__ void xcd_barrier(const XcdBarrier& b) {
;     ...
;             XB_SPIN(xb_ld(&bar[XB_XGEN(b.x)]) == gen, bar);
.LBB0_1822:
	global_load_dword v2, v0, s[16:17] sc1
	s_add_i32 s2, s2, 1
	s_mov_b64 s[38:39], -1
	s_waitcnt vmcnt(0)
	v_cmp_ge_u32_e32 vcc, v2, v20
	s_orn2_b64 s[36:37], vcc, exec
	s_branch .LBB0_1817

; __device__ __forceinline__ unsigned xb_ld(unsigned* p)              { return __hip_atomic_load(p, __ATOMIC_RELAXED, __HIP_MEMORY_SCOPE_AGENT); }
; __device__ __forceinline__ unsigned xb_add(unsigned* p, unsigned v) { return __hip_atomic_fetch_add(p, v, __ATOMIC_RELAXED, __HIP_MEMORY_SCOPE_AGENT); }
; #define XB_SPIN(cond, bar) do { unsigned _sp = 0; while (cond) { __builtin_amdgcn_s_sleep(1); \
;     if ((++_sp & 255u) == 0u) { if (xb_ld(&(bar)[XB_TMO])) break; if (_sp > XB_SPIN_CAP) { atomicAdd(&(bar)[XB_TMO], 1u); break; } } } } while (0)
; __device__ __forceinline__ void xcd_barrier(const XcdBarrier& b) {
;     ...
;             const unsigned og = xb_add(&bar[XB_TOP], 1u);
;             const unsigned tg = og / nx;
;             if (og + 1u == (tg + 1u) * nx) xb_add(&bar[XB_TOPGEN], 1u);
;             else XB_SPIN(xb_ld(&bar[XB_TOPGEN]) == tg, bar);
.LBB0_1831:
	s_or_b64 exec, exec, s[10:11]
	v_cvt_f32_u32_e32 v3, v0
	s_waitcnt vmcnt(0)
	v_readfirstlane_b32 s2, v2
	s_add_u32 s10, s26, 0xff03400
	s_addc_u32 s11, s27, 0
	v_rcp_iflag_f32_e32 v3, v3
	v_add_u32_e32 v1, s2, v1
	v_add_u32_e32 v4, 1, v1
	s_mov_b64 s[14:15], -1
	v_mul_f32_e32 v2, 0x4f7ffffe, v3
	v_cvt_u32_f32_e32 v2, v2
	v_sub_u32_e32 v3, 0, v0
	v_mul_lo_u32 v3, v3, v2
	v_mul_hi_u32 v3, v2, v3
	v_add_u32_e32 v2, v2, v3
	v_mul_hi_u32 v2, v1, v2
	v_mul_lo_u32 v3, v2, v0
	v_sub_u32_e32 v1, v1, v3
	v_add_u32_e32 v5, 1, v2
	v_cmp_ge_u32_e32 vcc, v1, v0
	v_sub_u32_e32 v3, v1, v0
	s_nop 0
	v_cndmask_b32_e32 v2, v2, v5, vcc
	v_cndmask_b32_e32 v1, v1, v3, vcc
	v_add_u32_e32 v3, 1, v2
	v_cmp_ge_u32_e32 vcc, v1, v0
	s_nop 1
	v_cndmask_b32_e32 v2, v2, v3, vcc
	v_mul_lo_u32 v1, v0, v2
	v_add_u32_e32 v0, v1, v0
	v_cmp_ne_u32_e32 vcc, v4, v0
	v_mov_b64_e32 v[0:1], s[10:11]
	s_and_saveexec_b64 s[8:9], vcc
	s_cbranch_execz .LBB0_1843
	v_mov_b32_e32 v20, v0
	v_mov_b32_e32 v0, 0
	global_load_dword v1, v0, s[10:11] sc1
	s_mov_b64 s[18:19], 0
	s_waitcnt vmcnt(0)
	v_cmp_lt_u32_e32 vcc, v1, v20
	s_and_saveexec_b64 s[16:17], vcc
	s_cbranch_execz .LBB0_1842
	s_add_u32 s14, s26, 0xff00200
	s_addc_u32 s15, s27, 0
	s_mov_b32 s2, 1
	s_branch .LBB0_1835

; __device__ __forceinline__ unsigned xb_ld(unsigned* p)              { return __hip_atomic_load(p, __ATOMIC_RELAXED, __HIP_MEMORY_SCOPE_AGENT); }
; #define XB_SPIN(cond, bar) do { unsigned _sp = 0; while (cond) { __builtin_amdgcn_s_sleep(1); \
;     if ((++_sp & 255u) == 0u) { if (xb_ld(&(bar)[XB_TMO])) break; if (_sp > XB_SPIN_CAP) { atomicAdd(&(bar)[XB_TMO], 1u); break; } } } } while (0)
; __device__ __forceinline__ void xcd_barrier(const XcdBarrier& b) {
;     ...
;             else XB_SPIN(xb_ld(&bar[XB_TOPGEN]) == tg, bar);
.LBB0_1839:
	global_load_dword v1, v0, s[10:11] sc1
	s_add_i32 s2, s2, 1
	s_mov_b64 s[36:37], -1
	s_waitcnt vmcnt(0)
	v_cmp_ge_u32_e32 vcc, v1, v20
	s_orn2_b64 s[40:41], vcc, exec
	s_branch .LBB0_1834

; __device__ __forceinline__ unsigned xb_ld(unsigned* p)              { return __hip_atomic_load(p, __ATOMIC_RELAXED, __HIP_MEMORY_SCOPE_AGENT); }
; __device__ __forceinline__ unsigned xb_add(unsigned* p, unsigned v) { return __hip_atomic_fetch_add(p, v, __ATOMIC_RELAXED, __HIP_MEMORY_SCOPE_AGENT); }
; #define XB_SPIN(cond, bar) do { unsigned _sp = 0; while (cond) { __builtin_amdgcn_s_sleep(1); \
;     if ((++_sp & 255u) == 0u) { if (xb_ld(&(bar)[XB_TMO])) break; if (_sp > XB_SPIN_CAP) { atomicAdd(&(bar)[XB_TMO], 1u); break; } } } } while (0)
; __device__ __forceinline__ void xcd_barrier(const XcdBarrier& b) {
;     ...
;             if (og + 1u == (tg + 1u) * nx) xb_add(&bar[XB_TOPGEN], 1u);
;             else XB_SPIN(xb_ld(&bar[XB_TOPGEN]) == tg, bar);
;             __builtin_amdgcn_fence(__ATOMIC_ACQUIRE, "agent");
;             xb_add(&bar[XB_XGEN(b.x)], 1u);
.LBB0_1843:
	s_or_b64 exec, exec, s[8:9]
	s_and_saveexec_b64 s[8:9], s[14:15]
	s_cbranch_execz .LBB0_1845
	v_mov_b32_e32 v2, 1
.LBB0_1845:
	s_or_b64 exec, exec, s[8:9]
	s_mov_b64 s[8:9], exec
	v_mbcnt_lo_u32_b32 v0, s8, 0
	v_mbcnt_hi_u32_b32 v0, s9, v0
	v_cmp_eq_u32_e32 vcc, 0, v0
	s_waitcnt vmcnt(0)
	s_and_saveexec_b64 s[10:11], vcc
	s_cbranch_execz .LBB0_1847
	s_bcnt1_i32_b64 s2, s[8:9]
	v_mov_b32_e32 v0, 0x2000
	v_mov_b32_e32 v1, s2
